# attention loop: all 8-byte instructions placed on 8-byte boundaries (e64 promotions, SGPR xor constants, precomputed m0 values)
# baseline (speedup 1.0000x reference)
.LBB0_877:
	s_or_b64 exec, exec, s[0:1]
	v_mov_b32_e32 v1, v254
	s_waitcnt lgkmcnt(0)
	s_barrier
	s_cmp_lg_u32 0, -1
	v_lshrrev_b32_e32 v5, 2, v1
	v_lshrrev_b32_e32 v2, 5, v1
	v_lshlrev_b32_e32 v4, 2, v1
	v_and_b32_e32 v6, 2, v5
	v_and_or_b32 v4, v4, 12, v6
	v_xor_b32_e32 v6, v2, v5
	v_and_or_b32 v4, v6, 1, v4
	v_lshrrev_b32_e32 v6, 1, v1
	v_and_b32_e32 v0, 31, v1
	v_xor_b32_e32 v2, v2, v6
	v_lshlrev_b32_e32 v7, 7, v0
	v_lshlrev_b32_e32 v2, 4, v2
	v_lshlrev_b32_e32 v6, 3, v1
	v_bfe_u32 v3, v1, 5, 1
	v_and_or_b32 v2, v2, 16, v7
	v_and_b32_e32 v7, 0x60, v6
	v_bfe_u32 v8, v1, 2, 2
	v_and_b32_e32 v6, 8, v6
	s_cselect_b32 s0, 0, 0
	v_lshrrev_b32_e32 v9, 3, v1
	v_lshlrev_b32_e32 v12, 10, v3
	v_lshlrev_b32_e32 v13, 8, v8
	v_add_u32_e32 v6, s0, v6
	v_and_b32_e32 v10, 2, v9
	v_bfe_u32 v11, v1, 1, 1
	v_add3_u32 v6, v6, v12, v13
	v_or_b32_e32 v13, 2, v3
	v_lshlrev_b32_e32 v0, 8, v0
	v_bitop3_b32 v12, v10, v3, v11 bitop3:0x36
	v_bitop3_b32 v10, v10, v13, v11 bitop3:0x36
	v_lshl_or_b32 v198, v4, 4, v0
	v_lshlrev_b32_e32 v0, 4, v1
	v_lshlrev_b32_e32 v10, 4, v10
	s_movk_i32 s0, 0x800
	v_lshlrev_b32_e32 v8, 6, v8
	s_movk_i32 s16, 0x4000
	v_and_b32_e32 v0, 0x1f0, v0
	v_lshl_add_u32 v12, v12, 4, v6
	v_add3_u32 v6, v6, v10, s0
	v_xor_b32_e32 v10, 64, v8
	v_or3_b32 v199, v2, v7, s16
	v_lshl_or_b32 v2, v3, 9, v0
	v_mov_b32_e32 v0, 0
	v_add_u32_e32 v188, v12, v8
	v_add_u32_e32 v189, v6, v8
	v_add_u32_e32 v192, v12, v10
	v_add_u32_e32 v193, v6, v10
	v_xor_b32_e32 v10, 0x80, v8
	v_xor_b32_e32 v8, 0xc0, v8
	v_mov_b32_e32 v3, v0
	v_add_u32_e32 v196, v12, v8
	v_add_u32_e32 v197, v6, v8
	v_lshl_add_u64 v[162:163], s[36:37], 0, v[2:3]
	v_and_b32_e32 v2, 15, v1
	v_and_b32_e32 v5, 12, v5
	v_bfe_u32 v8, v1, 6, 2
	v_bitop3_b32 v2, v5, v2, v8 bitop3:0x36
	s_not_b32 s0, s2
	v_add_u32_e32 v3, 0x200, v1
	v_lshrrev_b32_e32 v4, 4, v1
	v_lshlrev_b32_e32 v2, 4, v2
	s_movk_i32 s7, 0x180
	s_add_i32 s17, s30, s0
	v_mad_u64_u32 v[164:165], s[0:1], v4, s7, v[2:3]
	v_bfe_u32 v7, v1, 4, 5
	v_lshrrev_b32_e32 v5, 4, v3
	s_mov_b32 s0, 0x1ffffe0
	v_add_u32_e32 v195, v6, v10
	s_movk_i32 s6, 0xc0
	v_ashrrev_i32_e32 v6, 6, v1
	v_ashrrev_i32_e32 v200, 8, v1
	v_and_or_b32 v5, v5, s0, v7
	v_xor_b32_e32 v1, v4, v1
	v_mad_u64_u32 v[166:167], s[0:1], v5, s7, v[2:3]
	v_mul_lo_u32 v5, v9, s6
	v_lshlrev_b32_e32 v1, 3, v1
	v_and_or_b32 v1, v1, 56, v5
	v_mov_b32_e32 v5, 0x100
	v_lshlrev_b32_e32 v4, 10, v6
	v_lshl_add_u32 v168, v1, 1, v5
	v_lshrrev_b32_e32 v1, 9, v3
	v_mul_u32_u24_e32 v1, 0x3000, v1
	v_mul_u32_u24_e32 v3, 0x180, v7
	v_add_u32_e32 v203, 0, v4
	s_mov_b32 s3, 0
	v_add_u32_e32 v194, v12, v10
	v_and_b32_e32 v201, 3, v6
	v_bfe_u32 v202, v6, 1, 1
	v_mov_b32_e32 v165, v0
	v_mov_b32_e32 v167, v0
	v_mov_b32_e32 v169, v0
	s_movk_i32 s36, 0x3000
	v_add3_u32 v170, v1, v3, v2
	v_mov_b32_e32 v171, v0
	s_movk_i32 s37, 0x1000
	s_movk_i32 s40, 0x2000
	v_add_u32_e32 v204, 0x2000, v203
	v_add_u32_e32 v205, 0x4000, v203
	s_mov_b64 s[0:1], 0x1dc06000
	s_mov_b32 s41, 0x8000
	s_mov_b64 s[6:7], 0x1dc0c000
	s_movk_i32 s44, 0xfe0
	s_movk_i32 s45, 0x2200
	s_mov_b32 s50, 0xc000
	s_mov_b32 s51, 0x10000
	s_mov_b32 s52, 0x14000
	s_mov_b32 s53, 0x18000
	v_mbcnt_hi_u32_b32 v191, -1, v186
	v_readfirstlane_b32 s74, v203
	v_readfirstlane_b32 s76, v254
	s_nop 0
	s_bfe_u32 s76, s76, 0x10007
	s_add_u32 s82, s74, 0x6000
	s_add_u32 s83, s74, 0x8000
	s_add_u32 s86, s74, 0xa000
	s_add_u32 s87, s74, 0x2000
	s_add_u32 s88, s74, 0x4000
	s_movk_i32 s77, 0x60
	s_movk_i32 s78, 0x80
	s_movk_i32 s79, 0xa0
	s_movk_i32 s80, 0xc0
	s_movk_i32 s81, 0xe0
	s_mov_b32 s54, 0
	s_branch .LBB0_879

.LBB0_883:
	s_add_i32 s57, s57, 2
	s_and_b64 vcc, exec, s[12:13]
	s_add_u32 s8, s8, 0xc000
	s_addc_u32 s9, s9, 0
	s_waitcnt vmcnt(0) lgkmcnt(0)
	s_barrier
	s_cbranch_vccnz .LBB0_893
.LBB0_884:
	s_add_u32 s72, s8, s0
	s_addc_u32 s73, s9, s1
	s_mov_b32 m0, s82
	s_nop 0
	global_load_lds_dwordx4 v164, s[72:73]
	s_mov_b32 m0, s83
	s_nop 0
	global_load_lds_dwordx4 v170, s[72:73]
	s_mov_b32 m0, s86
	s_nop 0
	global_load_lds_dwordx4 v168, s[72:73]
	s_cmp_gt_u32 s57, s75
	s_cbranch_scc1 .LBB0_888
	ds_read_b128 v[146:149], v198
	ds_read_b128 v[150:153], v198 offset:8192
	v_xor_b32_e64 v209, 0x20, v198
	ds_read_b128 v[246:249], v209
	ds_read_b128 v[250:253], v209 offset:8192
	v_xor_b32_e64 v190, 0x40, v198
	ds_read_b128 v[180:183], v190
	ds_read_b128 v[184:187], v190 offset:8192
	v_xor_b32_e32 v209, s77, v198
	s_waitcnt lgkmcnt(4)
	v_mfma_f32_32x32x16_bf16 v[82:97], v[146:149], v[98:101], v[210:225]
	v_mfma_f32_32x32x16_bf16 v[66:81], v[150:153], v[98:101], v[210:225]
	ds_read_b128 v[146:149], v209
	ds_read_b128 v[150:153], v209 offset:8192
	v_xor_b32_e32 v190, s78, v198
	s_waitcnt lgkmcnt(4)
	v_mfma_f32_32x32x16_bf16 v[82:97], v[246:249], v[102:105], v[82:97]
	v_mfma_f32_32x32x16_bf16 v[66:81], v[250:253], v[102:105], v[66:81]
	ds_read_b128 v[246:249], v190
	ds_read_b128 v[250:253], v190 offset:8192
	v_xor_b32_e32 v209, s79, v198
	s_waitcnt lgkmcnt(4)
	v_mfma_f32_32x32x16_bf16 v[82:97], v[180:183], v[106:109], v[82:97]
	v_mfma_f32_32x32x16_bf16 v[66:81], v[184:187], v[106:109], v[66:81]
	ds_read_b128 v[180:183], v209
	ds_read_b128 v[184:187], v209 offset:8192
	v_xor_b32_e32 v190, s80, v198
	s_waitcnt lgkmcnt(4)
	v_mfma_f32_32x32x16_bf16 v[82:97], v[146:149], v[110:113], v[82:97]
	v_mfma_f32_32x32x16_bf16 v[66:81], v[150:153], v[110:113], v[66:81]
	ds_read_b128 v[146:149], v190
	ds_read_b128 v[150:153], v190 offset:8192
	v_xor_b32_e32 v209, s81, v198
	s_waitcnt lgkmcnt(4)
	v_mfma_f32_32x32x16_bf16 v[82:97], v[246:249], v[122:125], v[82:97]
	v_mfma_f32_32x32x16_bf16 v[66:81], v[250:253], v[122:125], v[66:81]
	ds_read_b128 v[246:249], v209
	ds_read_b128 v[250:253], v209 offset:8192
	s_waitcnt lgkmcnt(4)
	s_nop 0
	v_mfma_f32_32x32x16_bf16 v[82:97], v[180:183], v[114:117], v[82:97]
	v_mfma_f32_32x32x16_bf16 v[66:81], v[184:187], v[114:117], v[66:81]
	ds_read_b128 v[180:183], v199
	ds_read_b128 v[184:187], v199 offset:4096
	v_xor_b32_e32 v209, 0x20, v199
	s_waitcnt lgkmcnt(4)
	v_mfma_f32_32x32x16_bf16 v[82:97], v[146:149], v[118:121], v[82:97]
	v_mfma_f32_32x32x16_bf16 v[66:81], v[150:153], v[118:121], v[66:81]
	ds_read_b128 v[146:149], v209
	ds_read_b128 v[150:153], v209 offset:4096
	v_xor_b32_e32 v190, 0x40, v199
	s_waitcnt lgkmcnt(4)
	v_mfma_f32_32x32x16_bf16 v[82:97], v[246:249], v[126:129], v[82:97]
	v_mfma_f32_32x32x16_bf16 v[66:81], v[250:253], v[126:129], v[66:81]
	ds_read_b128 v[246:249], v190
	ds_read_b128 v[250:253], v190 offset:4096
	v_xor_b32_e32 v209, s77, v199
	s_waitcnt lgkmcnt(4)
	v_mfma_f32_32x32x16_bf16 v[82:97], v[180:183], v[130:133], v[82:97]
	v_mfma_f32_32x32x16_bf16 v[66:81], v[184:187], v[130:133], v[66:81]
	ds_read_b128 v[180:183], v209
	ds_read_b128 v[184:187], v209 offset:4096
	s_waitcnt lgkmcnt(4)
	s_nop 0
	v_mfma_f32_32x32x16_bf16 v[82:97], v[146:149], v[134:137], v[82:97]
	v_mfma_f32_32x32x16_bf16 v[66:81], v[150:153], v[134:137], v[66:81]
	s_waitcnt lgkmcnt(2)
	s_nop 0
	v_mfma_f32_32x32x16_bf16 v[82:97], v[246:249], v[138:141], v[82:97]
	v_mfma_f32_32x32x16_bf16 v[66:81], v[250:253], v[138:141], v[66:81]
	s_waitcnt lgkmcnt(0)
	s_nop 0
	v_mfma_f32_32x32x16_bf16 v[66:81], v[184:187], v[142:145], v[66:81]
	v_mfma_f32_32x32x16_bf16 v[82:97], v[180:183], v[142:145], v[82:97]
	ds_read_b64_tr_b16 v[158:159], v188 offset:0
	ds_read_b64_tr_b16 v[160:161], v189 offset:0
	ds_read_b64_tr_b16 v[154:155], v192 offset:0
	ds_read_b64_tr_b16 v[156:157], v193 offset:0
	ds_read_b64_tr_b16 v[150:151], v194 offset:0
	ds_read_b64_tr_b16 v[152:153], v195 offset:0
	ds_read_b64_tr_b16 v[146:147], v196 offset:0
	ds_read_b64_tr_b16 v[148:149], v197 offset:0
	s_nop 2
	s_nop 0
	v_max3_f32 v1, v66, v67, v68
	v_max3_f32 v180, v69, v70, v71
	v_max3_f32 v1, v1, v72, v73
	v_max3_f32 v180, v180, v74, v75
	v_max3_f32 v1, v1, v76, v77
	v_max3_f32 v180, v180, v78, v79
	v_max3_f32 v1, v1, v80, v81
	v_max3_f32 v181, v82, v83, v84
	v_max3_f32 v182, v85, v86, v87
	v_max3_f32 v181, v181, v88, v89
	v_max3_f32 v182, v182, v90, v91
	v_max3_f32 v181, v181, v92, v93
	v_max3_f32 v182, v182, v94, v95
	v_max3_f32 v181, v181, v96, v97
	v_max3_f32 v1, v1, v180, v181
	v_max_f32_e64 v1, v1, v182
	s_cmp_eq_u32 s57, 0
	s_cbranch_scc1 .Latt_rare0
	v_cmp_lt_f32_e32 vcc, 0x41000000, v1
	s_cbranch_vccz .Latt_common0
.Latt_rare0:
	v_mov_b32_e32 v180, v1
	s_nop 1
	v_permlane32_swap_b32_e32 v1, v180
	v_max_f32_e32 v1, v1, v180
	s_cmp_eq_u32 s57, 0
	s_cselect_b32 s71, 0xf149f2ca, 0
	v_max_f32_e64 v243, v1, s71
	v_max_f32_e64 v242, 0, v1
	v_exp_f32_e64 v242, -v242
	v_sub_f32_e32 v210, v210, v243
	v_sub_f32_e32 v211, v211, v243
	v_sub_f32_e32 v212, v212, v243
	v_sub_f32_e32 v213, v213, v243
	v_sub_f32_e32 v214, v214, v243
	v_sub_f32_e32 v215, v215, v243
	v_sub_f32_e32 v216, v216, v243
	v_sub_f32_e32 v217, v217, v243
	v_sub_f32_e32 v218, v218, v243
	v_sub_f32_e32 v219, v219, v243
	v_sub_f32_e32 v220, v220, v243
	v_sub_f32_e32 v221, v221, v243
	v_sub_f32_e32 v222, v222, v243
	v_sub_f32_e32 v223, v223, v243
	v_sub_f32_e32 v224, v224, v243
	v_sub_f32_e32 v225, v225, v243
	v_sub_f32_e32 v66, v66, v243
	v_sub_f32_e32 v67, v67, v243
	v_sub_f32_e32 v68, v68, v243
	v_sub_f32_e32 v69, v69, v243
	v_sub_f32_e32 v70, v70, v243
	v_sub_f32_e32 v71, v71, v243
	v_sub_f32_e32 v72, v72, v243
	v_sub_f32_e32 v73, v73, v243
	v_sub_f32_e32 v74, v74, v243
	v_sub_f32_e32 v75, v75, v243
	v_sub_f32_e32 v76, v76, v243
	v_sub_f32_e32 v77, v77, v243
	v_sub_f32_e32 v78, v78, v243
	v_sub_f32_e32 v79, v79, v243
	v_sub_f32_e32 v80, v80, v243
	v_sub_f32_e32 v81, v81, v243
	v_sub_f32_e32 v82, v82, v243
	v_sub_f32_e32 v83, v83, v243
	v_sub_f32_e32 v84, v84, v243
	v_sub_f32_e32 v85, v85, v243
	v_sub_f32_e32 v86, v86, v243
	v_sub_f32_e32 v87, v87, v243
	v_sub_f32_e32 v88, v88, v243
	v_sub_f32_e32 v89, v89, v243
	v_sub_f32_e32 v90, v90, v243
	v_sub_f32_e32 v91, v91, v243
	v_sub_f32_e32 v92, v92, v243
	v_sub_f32_e32 v93, v93, v243
	v_sub_f32_e32 v94, v94, v243
	v_sub_f32_e32 v95, v95, v243
	v_sub_f32_e32 v96, v96, v243
	v_sub_f32_e32 v97, v97, v243
	v_mul_f32_e64 v173, v173, v242
	v_pk_mul_f32 v[64:65], v[64:65], v[242:243] op_sel_hi:[1,0]
	v_pk_mul_f32 v[62:63], v[62:63], v[242:243] op_sel_hi:[1,0]
	v_pk_mul_f32 v[60:61], v[60:61], v[242:243] op_sel_hi:[1,0]
	v_pk_mul_f32 v[58:59], v[58:59], v[242:243] op_sel_hi:[1,0]
	v_pk_mul_f32 v[56:57], v[56:57], v[242:243] op_sel_hi:[1,0]
	v_pk_mul_f32 v[54:55], v[54:55], v[242:243] op_sel_hi:[1,0]
	v_pk_mul_f32 v[52:53], v[52:53], v[242:243] op_sel_hi:[1,0]
	v_pk_mul_f32 v[50:51], v[50:51], v[242:243] op_sel_hi:[1,0]
	v_pk_mul_f32 v[48:49], v[48:49], v[242:243] op_sel_hi:[1,0]
	v_pk_mul_f32 v[46:47], v[46:47], v[242:243] op_sel_hi:[1,0]
	v_pk_mul_f32 v[44:45], v[44:45], v[242:243] op_sel_hi:[1,0]
	v_pk_mul_f32 v[42:43], v[42:43], v[242:243] op_sel_hi:[1,0]
	v_pk_mul_f32 v[40:41], v[40:41], v[242:243] op_sel_hi:[1,0]
	v_pk_mul_f32 v[38:39], v[38:39], v[242:243] op_sel_hi:[1,0]
	v_pk_mul_f32 v[36:37], v[36:37], v[242:243] op_sel_hi:[1,0]
	v_pk_mul_f32 v[34:35], v[34:35], v[242:243] op_sel_hi:[1,0]
	v_pk_mul_f32 v[32:33], v[32:33], v[242:243] op_sel_hi:[1,0]
	v_pk_mul_f32 v[30:31], v[30:31], v[242:243] op_sel_hi:[1,0]
	v_pk_mul_f32 v[28:29], v[28:29], v[242:243] op_sel_hi:[1,0]
	v_pk_mul_f32 v[26:27], v[26:27], v[242:243] op_sel_hi:[1,0]
	v_pk_mul_f32 v[24:25], v[24:25], v[242:243] op_sel_hi:[1,0]
	v_pk_mul_f32 v[22:23], v[22:23], v[242:243] op_sel_hi:[1,0]
	v_pk_mul_f32 v[20:21], v[20:21], v[242:243] op_sel_hi:[1,0]
	v_pk_mul_f32 v[18:19], v[18:19], v[242:243] op_sel_hi:[1,0]
	v_pk_mul_f32 v[16:17], v[16:17], v[242:243] op_sel_hi:[1,0]
	v_pk_mul_f32 v[14:15], v[14:15], v[242:243] op_sel_hi:[1,0]
	v_pk_mul_f32 v[12:13], v[12:13], v[242:243] op_sel_hi:[1,0]
	v_pk_mul_f32 v[10:11], v[10:11], v[242:243] op_sel_hi:[1,0]
	v_pk_mul_f32 v[8:9], v[8:9], v[242:243] op_sel_hi:[1,0]
	v_pk_mul_f32 v[6:7], v[6:7], v[242:243] op_sel_hi:[1,0]
	v_pk_mul_f32 v[4:5], v[4:5], v[242:243] op_sel_hi:[1,0]
	v_pk_mul_f32 v[2:3], v[2:3], v[242:243] op_sel_hi:[1,0]
.Latt_common0:
	v_exp_f32_e32 v82, v82
	v_exp_f32_e32 v83, v83
	v_exp_f32_e32 v84, v84
	v_add_f32_e32 v173, v173, v82
	v_exp_f32_e32 v85, v85
	v_mov_b32_e32 v242, v83
	v_cvt_pk_bf16_f32 v82, v82, v83
	v_exp_f32_e32 v86, v86
	v_add_f32_e32 v173, v173, v84
	v_exp_f32_e32 v87, v87
	v_add_f32_e32 v242, v242, v85
	v_cvt_pk_bf16_f32 v83, v84, v85
	v_exp_f32_e32 v88, v88
	v_add_f32_e32 v173, v173, v86
	v_exp_f32_e32 v89, v89
	v_add_f32_e32 v242, v242, v87
	v_cvt_pk_bf16_f32 v84, v86, v87
	v_add_f32_e32 v173, v173, v88
	v_add_f32_e32 v242, v242, v89
	v_cvt_pk_bf16_f32 v85, v88, v89
	ds_read_b64_tr_b16 v[238:239], v188 offset:0x1000
	ds_read_b64_tr_b16 v[240:241], v189 offset:0x1000
	ds_read_b64_tr_b16 v[234:235], v192 offset:0x1000
	ds_read_b64_tr_b16 v[236:237], v193 offset:0x1000
	ds_read_b64_tr_b16 v[230:231], v194 offset:0x1000
	ds_read_b64_tr_b16 v[232:233], v195 offset:0x1000
	ds_read_b64_tr_b16 v[226:227], v196 offset:0x1000
	ds_read_b64_tr_b16 v[228:229], v197 offset:0x1000
	v_exp_f32_e32 v90, v90
	s_waitcnt lgkmcnt(8)
	v_mfma_f32_32x32x16_bf16 v[50:65], v[158:161], v[82:85], v[50:65]
	v_exp_f32_e32 v91, v91
	v_exp_f32_e32 v92, v92
	v_add_f32_e32 v173, v173, v90
	v_exp_f32_e32 v93, v93
	v_mfma_f32_32x32x16_bf16 v[34:49], v[154:157], v[82:85], v[34:49]
	v_add_f32_e64 v242, v242, v91
	v_cvt_pk_bf16_f32 v90, v90, v91
	v_exp_f32_e32 v94, v94
	v_add_f32_e32 v173, v173, v92
	v_exp_f32_e64 v95, v95
	v_mfma_f32_32x32x16_bf16 v[18:33], v[150:153], v[82:85], v[18:33]
	v_add_f32_e64 v242, v242, v93
	v_cvt_pk_bf16_f32 v91, v92, v93
	v_exp_f32_e32 v96, v96
	v_add_f32_e32 v173, v173, v94
	v_exp_f32_e64 v97, v97
	v_mfma_f32_32x32x16_bf16 v[2:17], v[146:149], v[82:85], v[2:17]
	v_add_f32_e64 v242, v242, v95
	v_cvt_pk_bf16_f32 v92, v94, v95
	v_add_f32_e32 v173, v173, v96
	v_add_f32_e32 v242, v242, v97
	v_cvt_pk_bf16_f32 v93, v96, v97
	ds_read_b64_tr_b16 v[158:159], v188 offset:0x2000
	ds_read_b64_tr_b16 v[160:161], v189 offset:0x2000
	ds_read_b64_tr_b16 v[154:155], v192 offset:0x2000
	ds_read_b64_tr_b16 v[156:157], v193 offset:0x2000
	ds_read_b64_tr_b16 v[150:151], v194 offset:0x2000
	ds_read_b64_tr_b16 v[152:153], v195 offset:0x2000
	ds_read_b64_tr_b16 v[146:147], v196 offset:0x2000
	ds_read_b64_tr_b16 v[148:149], v197 offset:0x2000
	v_exp_f32_e32 v66, v66
	s_waitcnt lgkmcnt(8)
	v_mfma_f32_32x32x16_bf16 v[50:65], v[238:241], v[90:93], v[50:65]
	v_exp_f32_e32 v67, v67
	v_exp_f32_e32 v68, v68
	v_add_f32_e32 v173, v173, v66
	v_exp_f32_e32 v69, v69
	v_mfma_f32_32x32x16_bf16 v[34:49], v[234:237], v[90:93], v[34:49]
	v_add_f32_e64 v242, v242, v67
	v_cvt_pk_bf16_f32 v66, v66, v67
	v_exp_f32_e32 v70, v70
	v_add_f32_e32 v173, v173, v68
	v_exp_f32_e64 v71, v71
	v_mfma_f32_32x32x16_bf16 v[18:33], v[230:233], v[90:93], v[18:33]
	v_add_f32_e64 v242, v242, v69
	v_cvt_pk_bf16_f32 v67, v68, v69
	v_exp_f32_e32 v72, v72
	v_add_f32_e32 v173, v173, v70
	v_exp_f32_e64 v73, v73
	v_mfma_f32_32x32x16_bf16 v[2:17], v[226:229], v[90:93], v[2:17]
	v_add_f32_e64 v242, v242, v71
	v_cvt_pk_bf16_f32 v68, v70, v71
	v_add_f32_e32 v173, v173, v72
	v_add_f32_e32 v242, v242, v73
	v_cvt_pk_bf16_f32 v69, v72, v73
	ds_read_b64_tr_b16 v[238:239], v188 offset:0x3000
	ds_read_b64_tr_b16 v[240:241], v189 offset:0x3000
	ds_read_b64_tr_b16 v[234:235], v192 offset:0x3000
	ds_read_b64_tr_b16 v[236:237], v193 offset:0x3000
	ds_read_b64_tr_b16 v[230:231], v194 offset:0x3000
	ds_read_b64_tr_b16 v[232:233], v195 offset:0x3000
	ds_read_b64_tr_b16 v[226:227], v196 offset:0x3000
	ds_read_b64_tr_b16 v[228:229], v197 offset:0x3000
	v_exp_f32_e32 v74, v74
	s_waitcnt lgkmcnt(8)
	v_mfma_f32_32x32x16_bf16 v[50:65], v[158:161], v[66:69], v[50:65]
	v_exp_f32_e32 v75, v75
	v_exp_f32_e32 v76, v76
	v_add_f32_e32 v173, v173, v74
	v_exp_f32_e32 v77, v77
	v_mfma_f32_32x32x16_bf16 v[34:49], v[154:157], v[66:69], v[34:49]
	v_add_f32_e64 v242, v242, v75
	v_cvt_pk_bf16_f32 v74, v74, v75
	v_exp_f32_e32 v78, v78
	v_add_f32_e32 v173, v173, v76
	v_exp_f32_e64 v79, v79
	v_mfma_f32_32x32x16_bf16 v[18:33], v[150:153], v[66:69], v[18:33]
	v_add_f32_e64 v242, v242, v77
	v_cvt_pk_bf16_f32 v75, v76, v77
	v_exp_f32_e32 v80, v80
	v_add_f32_e32 v173, v173, v78
	v_exp_f32_e64 v81, v81
	v_mfma_f32_32x32x16_bf16 v[2:17], v[146:149], v[66:69], v[2:17]
	v_add_f32_e64 v242, v242, v79
	v_cvt_pk_bf16_f32 v76, v78, v79
	v_add_f32_e32 v173, v173, v80
	v_add_f32_e32 v242, v242, v81
	v_cvt_pk_bf16_f32 v77, v80, v81
	s_waitcnt lgkmcnt(0)
	v_add_f32_e32 v173, v173, v242
	v_mfma_f32_32x32x16_bf16 v[50:65], v[238:241], v[74:77], v[50:65]
	v_mfma_f32_32x32x16_bf16 v[34:49], v[234:237], v[74:77], v[34:49]
	v_mfma_f32_32x32x16_bf16 v[18:33], v[230:233], v[74:77], v[18:33]
	v_mfma_f32_32x32x16_bf16 v[2:17], v[226:229], v[74:77], v[2:17]
.LBB0_888:
	s_cmp_ge_u32 s57, s56
	s_cselect_b64 s[12:13], -1, 0
	s_and_b64 vcc, exec, s[12:13]
	s_waitcnt vmcnt(0) lgkmcnt(0)
	s_barrier
	s_cbranch_vccnz .LBB0_890
	s_add_u32 s72, s8, s6
	s_addc_u32 s73, s9, s7
	s_mov_b32 m0, s74
	s_nop 0
	global_load_lds_dwordx4 v164, s[72:73]
	s_mov_b32 m0, s87
	s_nop 0
	global_load_lds_dwordx4 v170, s[72:73]
	s_mov_b32 m0, s88
	s_nop 0
	global_load_lds_dwordx4 v168, s[72:73]
.LBB0_890:
	s_cmp_ge_u32 s57, s75
	s_cbranch_scc1 .LBB0_883
	ds_read_b128 v[146:149], v198 offset:24576
	ds_read_b128 v[150:153], v198 offset:32768
	v_xor_b32_e64 v209, 0x20, v198
	ds_read_b128 v[246:249], v209 offset:24576
	ds_read_b128 v[250:253], v209 offset:32768
	v_xor_b32_e64 v190, 0x40, v198
	ds_read_b128 v[180:183], v190 offset:24576
	ds_read_b128 v[184:187], v190 offset:32768
	v_xor_b32_e32 v209, s77, v198
	s_waitcnt lgkmcnt(4)
	v_mfma_f32_32x32x16_bf16 v[82:97], v[146:149], v[98:101], v[210:225]
	v_mfma_f32_32x32x16_bf16 v[66:81], v[150:153], v[98:101], v[210:225]
	ds_read_b128 v[146:149], v209 offset:24576
	ds_read_b128 v[150:153], v209 offset:32768
	v_xor_b32_e32 v190, s78, v198
	s_waitcnt lgkmcnt(4)
	v_mfma_f32_32x32x16_bf16 v[82:97], v[246:249], v[102:105], v[82:97]
	v_mfma_f32_32x32x16_bf16 v[66:81], v[250:253], v[102:105], v[66:81]
	ds_read_b128 v[246:249], v190 offset:24576
	ds_read_b128 v[250:253], v190 offset:32768
	v_xor_b32_e32 v209, s79, v198
	s_waitcnt lgkmcnt(4)
	v_mfma_f32_32x32x16_bf16 v[82:97], v[180:183], v[106:109], v[82:97]
	v_mfma_f32_32x32x16_bf16 v[66:81], v[184:187], v[106:109], v[66:81]
	ds_read_b128 v[180:183], v209 offset:24576
	ds_read_b128 v[184:187], v209 offset:32768
	v_xor_b32_e32 v190, s80, v198
	s_waitcnt lgkmcnt(4)
	v_mfma_f32_32x32x16_bf16 v[82:97], v[146:149], v[110:113], v[82:97]
	v_mfma_f32_32x32x16_bf16 v[66:81], v[150:153], v[110:113], v[66:81]
	ds_read_b128 v[146:149], v190 offset:24576
	ds_read_b128 v[150:153], v190 offset:32768
	v_xor_b32_e32 v209, s81, v198
	s_waitcnt lgkmcnt(4)
	v_mfma_f32_32x32x16_bf16 v[82:97], v[246:249], v[122:125], v[82:97]
	v_mfma_f32_32x32x16_bf16 v[66:81], v[250:253], v[122:125], v[66:81]
	ds_read_b128 v[246:249], v209 offset:24576
	ds_read_b128 v[250:253], v209 offset:32768
	s_waitcnt lgkmcnt(4)
	s_nop 0
	v_mfma_f32_32x32x16_bf16 v[82:97], v[180:183], v[114:117], v[82:97]
	v_mfma_f32_32x32x16_bf16 v[66:81], v[184:187], v[114:117], v[66:81]
	ds_read_b128 v[180:183], v199 offset:24576
	ds_read_b128 v[184:187], v199 offset:28672
	v_xor_b32_e32 v209, 0x20, v199
	s_waitcnt lgkmcnt(4)
	v_mfma_f32_32x32x16_bf16 v[82:97], v[146:149], v[118:121], v[82:97]
	v_mfma_f32_32x32x16_bf16 v[66:81], v[150:153], v[118:121], v[66:81]
	ds_read_b128 v[146:149], v209 offset:24576
	ds_read_b128 v[150:153], v209 offset:28672
	v_xor_b32_e32 v190, 0x40, v199
	s_waitcnt lgkmcnt(4)
	v_mfma_f32_32x32x16_bf16 v[82:97], v[246:249], v[126:129], v[82:97]
	v_mfma_f32_32x32x16_bf16 v[66:81], v[250:253], v[126:129], v[66:81]
	ds_read_b128 v[246:249], v190 offset:24576
	ds_read_b128 v[250:253], v190 offset:28672
	v_xor_b32_e32 v209, s77, v199
	s_waitcnt lgkmcnt(4)
	v_mfma_f32_32x32x16_bf16 v[82:97], v[180:183], v[130:133], v[82:97]
	v_mfma_f32_32x32x16_bf16 v[66:81], v[184:187], v[130:133], v[66:81]
	ds_read_b128 v[180:183], v209 offset:24576
	ds_read_b128 v[184:187], v209 offset:28672
	s_waitcnt lgkmcnt(4)
	s_nop 0
	v_mfma_f32_32x32x16_bf16 v[82:97], v[146:149], v[134:137], v[82:97]
	v_mfma_f32_32x32x16_bf16 v[66:81], v[150:153], v[134:137], v[66:81]
	s_waitcnt lgkmcnt(2)
	s_nop 0
	v_mfma_f32_32x32x16_bf16 v[82:97], v[246:249], v[138:141], v[82:97]
	v_mfma_f32_32x32x16_bf16 v[66:81], v[250:253], v[138:141], v[66:81]
	s_waitcnt lgkmcnt(0)
	s_nop 0
	v_mfma_f32_32x32x16_bf16 v[66:81], v[184:187], v[142:145], v[66:81]
	v_mfma_f32_32x32x16_bf16 v[82:97], v[180:183], v[142:145], v[82:97]
	ds_read_b64_tr_b16 v[158:159], v188 offset:0x6000
	ds_read_b64_tr_b16 v[160:161], v189 offset:0x6000
	ds_read_b64_tr_b16 v[154:155], v192 offset:0x6000
	ds_read_b64_tr_b16 v[156:157], v193 offset:0x6000
	ds_read_b64_tr_b16 v[150:151], v194 offset:0x6000
	ds_read_b64_tr_b16 v[152:153], v195 offset:0x6000
	ds_read_b64_tr_b16 v[146:147], v196 offset:0x6000
	ds_read_b64_tr_b16 v[148:149], v197 offset:0x6000
	s_nop 2
	s_nop 0
	v_max3_f32 v1, v66, v67, v68
	v_max3_f32 v180, v69, v70, v71
	v_max3_f32 v1, v1, v72, v73
	v_max3_f32 v180, v180, v74, v75
	v_max3_f32 v1, v1, v76, v77
	v_max3_f32 v180, v180, v78, v79
	v_max3_f32 v1, v1, v80, v81
	v_max3_f32 v181, v82, v83, v84
	v_max3_f32 v182, v85, v86, v87
	v_max3_f32 v181, v181, v88, v89
	v_max3_f32 v182, v182, v90, v91
	v_max3_f32 v181, v181, v92, v93
	v_max3_f32 v182, v182, v94, v95
	v_max3_f32 v181, v181, v96, v97
	v_max3_f32 v1, v1, v180, v181
	v_max_f32_e64 v1, v1, v182
	v_cmp_lt_f32_e32 vcc, 0x41000000, v1
	s_cbranch_vccz .Latt_common1
.Latt_rare1:
	v_mov_b32_e32 v180, v1
	s_nop 1
	v_permlane32_swap_b32_e32 v1, v180
	v_max_f32_e32 v1, v1, v180
	v_max_f32_e32 v243, 0, v1
	v_max_f32_e64 v242, 0, v1
	v_exp_f32_e64 v242, -v242
	v_sub_f32_e32 v210, v210, v243
	v_sub_f32_e32 v211, v211, v243
	v_sub_f32_e32 v212, v212, v243
	v_sub_f32_e32 v213, v213, v243
	v_sub_f32_e32 v214, v214, v243
	v_sub_f32_e32 v215, v215, v243
	v_sub_f32_e32 v216, v216, v243
	v_sub_f32_e32 v217, v217, v243
	v_sub_f32_e32 v218, v218, v243
	v_sub_f32_e32 v219, v219, v243
	v_sub_f32_e32 v220, v220, v243
	v_sub_f32_e32 v221, v221, v243
	v_sub_f32_e32 v222, v222, v243
	v_sub_f32_e32 v223, v223, v243
	v_sub_f32_e32 v224, v224, v243
	v_sub_f32_e32 v225, v225, v243
	v_sub_f32_e32 v66, v66, v243
	v_sub_f32_e32 v67, v67, v243
	v_sub_f32_e32 v68, v68, v243
	v_sub_f32_e32 v69, v69, v243
	v_sub_f32_e32 v70, v70, v243
	v_sub_f32_e32 v71, v71, v243
	v_sub_f32_e32 v72, v72, v243
	v_sub_f32_e32 v73, v73, v243
	v_sub_f32_e32 v74, v74, v243
	v_sub_f32_e32 v75, v75, v243
	v_sub_f32_e32 v76, v76, v243
	v_sub_f32_e32 v77, v77, v243
	v_sub_f32_e32 v78, v78, v243
	v_sub_f32_e32 v79, v79, v243
	v_sub_f32_e32 v80, v80, v243
	v_sub_f32_e32 v81, v81, v243
	v_sub_f32_e32 v82, v82, v243
	v_sub_f32_e32 v83, v83, v243
	v_sub_f32_e32 v84, v84, v243
	v_sub_f32_e32 v85, v85, v243
	v_sub_f32_e32 v86, v86, v243
	v_sub_f32_e32 v87, v87, v243
	v_sub_f32_e32 v88, v88, v243
	v_sub_f32_e32 v89, v89, v243
	v_sub_f32_e32 v90, v90, v243
	v_sub_f32_e32 v91, v91, v243
	v_sub_f32_e32 v92, v92, v243
	v_sub_f32_e32 v93, v93, v243
	v_sub_f32_e32 v94, v94, v243
	v_sub_f32_e32 v95, v95, v243
	v_sub_f32_e32 v96, v96, v243
	v_sub_f32_e32 v97, v97, v243
	v_mul_f32_e64 v173, v173, v242
	v_pk_mul_f32 v[64:65], v[64:65], v[242:243] op_sel_hi:[1,0]
	v_pk_mul_f32 v[62:63], v[62:63], v[242:243] op_sel_hi:[1,0]
	v_pk_mul_f32 v[60:61], v[60:61], v[242:243] op_sel_hi:[1,0]
	v_pk_mul_f32 v[58:59], v[58:59], v[242:243] op_sel_hi:[1,0]
	v_pk_mul_f32 v[56:57], v[56:57], v[242:243] op_sel_hi:[1,0]
	v_pk_mul_f32 v[54:55], v[54:55], v[242:243] op_sel_hi:[1,0]
	v_pk_mul_f32 v[52:53], v[52:53], v[242:243] op_sel_hi:[1,0]
	v_pk_mul_f32 v[50:51], v[50:51], v[242:243] op_sel_hi:[1,0]
	v_pk_mul_f32 v[48:49], v[48:49], v[242:243] op_sel_hi:[1,0]
	v_pk_mul_f32 v[46:47], v[46:47], v[242:243] op_sel_hi:[1,0]
	v_pk_mul_f32 v[44:45], v[44:45], v[242:243] op_sel_hi:[1,0]
	v_pk_mul_f32 v[42:43], v[42:43], v[242:243] op_sel_hi:[1,0]
	v_pk_mul_f32 v[40:41], v[40:41], v[242:243] op_sel_hi:[1,0]
	v_pk_mul_f32 v[38:39], v[38:39], v[242:243] op_sel_hi:[1,0]
	v_pk_mul_f32 v[36:37], v[36:37], v[242:243] op_sel_hi:[1,0]
	v_pk_mul_f32 v[34:35], v[34:35], v[242:243] op_sel_hi:[1,0]
	v_pk_mul_f32 v[32:33], v[32:33], v[242:243] op_sel_hi:[1,0]
	v_pk_mul_f32 v[30:31], v[30:31], v[242:243] op_sel_hi:[1,0]
	v_pk_mul_f32 v[28:29], v[28:29], v[242:243] op_sel_hi:[1,0]
	v_pk_mul_f32 v[26:27], v[26:27], v[242:243] op_sel_hi:[1,0]
	v_pk_mul_f32 v[24:25], v[24:25], v[242:243] op_sel_hi:[1,0]
	v_pk_mul_f32 v[22:23], v[22:23], v[242:243] op_sel_hi:[1,0]
	v_pk_mul_f32 v[20:21], v[20:21], v[242:243] op_sel_hi:[1,0]
	v_pk_mul_f32 v[18:19], v[18:19], v[242:243] op_sel_hi:[1,0]
	v_pk_mul_f32 v[16:17], v[16:17], v[242:243] op_sel_hi:[1,0]
	v_pk_mul_f32 v[14:15], v[14:15], v[242:243] op_sel_hi:[1,0]
	v_pk_mul_f32 v[12:13], v[12:13], v[242:243] op_sel_hi:[1,0]
	v_pk_mul_f32 v[10:11], v[10:11], v[242:243] op_sel_hi:[1,0]
	v_pk_mul_f32 v[8:9], v[8:9], v[242:243] op_sel_hi:[1,0]
	v_pk_mul_f32 v[6:7], v[6:7], v[242:243] op_sel_hi:[1,0]
	v_pk_mul_f32 v[4:5], v[4:5], v[242:243] op_sel_hi:[1,0]
	v_pk_mul_f32 v[2:3], v[2:3], v[242:243] op_sel_hi:[1,0]
.Latt_common1:
	v_exp_f32_e32 v82, v82
	v_exp_f32_e32 v83, v83
	v_exp_f32_e32 v84, v84
	v_add_f32_e32 v173, v173, v82
	v_exp_f32_e32 v85, v85
	v_mov_b32_e32 v242, v83
	v_cvt_pk_bf16_f32 v82, v82, v83
	v_exp_f32_e32 v86, v86
	v_add_f32_e32 v173, v173, v84
	v_exp_f32_e32 v87, v87
	v_add_f32_e32 v242, v242, v85
	v_cvt_pk_bf16_f32 v83, v84, v85
	v_exp_f32_e32 v88, v88
	v_add_f32_e32 v173, v173, v86
	v_exp_f32_e32 v89, v89
	v_add_f32_e32 v242, v242, v87
	v_cvt_pk_bf16_f32 v84, v86, v87
	v_add_f32_e32 v173, v173, v88
	v_add_f32_e32 v242, v242, v89
	v_cvt_pk_bf16_f32 v85, v88, v89
	ds_read_b64_tr_b16 v[238:239], v188 offset:0x7000
	ds_read_b64_tr_b16 v[240:241], v189 offset:0x7000
	ds_read_b64_tr_b16 v[234:235], v192 offset:0x7000
	ds_read_b64_tr_b16 v[236:237], v193 offset:0x7000
	ds_read_b64_tr_b16 v[230:231], v194 offset:0x7000
	ds_read_b64_tr_b16 v[232:233], v195 offset:0x7000
	ds_read_b64_tr_b16 v[226:227], v196 offset:0x7000
	ds_read_b64_tr_b16 v[228:229], v197 offset:0x7000
	v_exp_f32_e32 v90, v90
	s_waitcnt lgkmcnt(8)
	v_mfma_f32_32x32x16_bf16 v[50:65], v[158:161], v[82:85], v[50:65]
	v_exp_f32_e32 v91, v91
	v_exp_f32_e32 v92, v92
	v_add_f32_e32 v173, v173, v90
	v_exp_f32_e32 v93, v93
	v_mfma_f32_32x32x16_bf16 v[34:49], v[154:157], v[82:85], v[34:49]
	v_add_f32_e64 v242, v242, v91
	v_cvt_pk_bf16_f32 v90, v90, v91
	v_exp_f32_e32 v94, v94
	v_add_f32_e32 v173, v173, v92
	v_exp_f32_e64 v95, v95
	v_mfma_f32_32x32x16_bf16 v[18:33], v[150:153], v[82:85], v[18:33]
	v_add_f32_e64 v242, v242, v93
	v_cvt_pk_bf16_f32 v91, v92, v93
	v_exp_f32_e32 v96, v96
	v_add_f32_e32 v173, v173, v94
	v_exp_f32_e64 v97, v97
	v_mfma_f32_32x32x16_bf16 v[2:17], v[146:149], v[82:85], v[2:17]
	v_add_f32_e64 v242, v242, v95
	v_cvt_pk_bf16_f32 v92, v94, v95
	v_add_f32_e32 v173, v173, v96
	v_add_f32_e32 v242, v242, v97
	v_cvt_pk_bf16_f32 v93, v96, v97
	ds_read_b64_tr_b16 v[158:159], v188 offset:0x8000
	ds_read_b64_tr_b16 v[160:161], v189 offset:0x8000
	ds_read_b64_tr_b16 v[154:155], v192 offset:0x8000
	ds_read_b64_tr_b16 v[156:157], v193 offset:0x8000
	ds_read_b64_tr_b16 v[150:151], v194 offset:0x8000
	ds_read_b64_tr_b16 v[152:153], v195 offset:0x8000
	ds_read_b64_tr_b16 v[146:147], v196 offset:0x8000
	ds_read_b64_tr_b16 v[148:149], v197 offset:0x8000
	v_exp_f32_e32 v66, v66
	s_waitcnt lgkmcnt(8)
	v_mfma_f32_32x32x16_bf16 v[50:65], v[238:241], v[90:93], v[50:65]
	v_exp_f32_e32 v67, v67
	v_exp_f32_e32 v68, v68
	v_add_f32_e32 v173, v173, v66
	v_exp_f32_e32 v69, v69
	v_mfma_f32_32x32x16_bf16 v[34:49], v[234:237], v[90:93], v[34:49]
	v_add_f32_e64 v242, v242, v67
	v_cvt_pk_bf16_f32 v66, v66, v67
	v_exp_f32_e32 v70, v70
	v_add_f32_e32 v173, v173, v68
	v_exp_f32_e64 v71, v71
	v_mfma_f32_32x32x16_bf16 v[18:33], v[230:233], v[90:93], v[18:33]
	v_add_f32_e64 v242, v242, v69
	v_cvt_pk_bf16_f32 v67, v68, v69
	v_exp_f32_e32 v72, v72
	v_add_f32_e32 v173, v173, v70
	v_exp_f32_e64 v73, v73
	v_mfma_f32_32x32x16_bf16 v[2:17], v[226:229], v[90:93], v[2:17]
	v_add_f32_e64 v242, v242, v71
	v_cvt_pk_bf16_f32 v68, v70, v71
	v_add_f32_e32 v173, v173, v72
	v_add_f32_e32 v242, v242, v73
	v_cvt_pk_bf16_f32 v69, v72, v73
	ds_read_b64_tr_b16 v[238:239], v188 offset:0x9000
	ds_read_b64_tr_b16 v[240:241], v189 offset:0x9000
	ds_read_b64_tr_b16 v[234:235], v192 offset:0x9000
	ds_read_b64_tr_b16 v[236:237], v193 offset:0x9000
	ds_read_b64_tr_b16 v[230:231], v194 offset:0x9000
	ds_read_b64_tr_b16 v[232:233], v195 offset:0x9000
	ds_read_b64_tr_b16 v[226:227], v196 offset:0x9000
	ds_read_b64_tr_b16 v[228:229], v197 offset:0x9000
	v_exp_f32_e32 v74, v74
	s_waitcnt lgkmcnt(8)
	v_mfma_f32_32x32x16_bf16 v[50:65], v[158:161], v[66:69], v[50:65]
	v_exp_f32_e32 v75, v75
	v_exp_f32_e32 v76, v76
	v_add_f32_e32 v173, v173, v74
	v_exp_f32_e32 v77, v77
	v_mfma_f32_32x32x16_bf16 v[34:49], v[154:157], v[66:69], v[34:49]
	v_add_f32_e64 v242, v242, v75
	v_cvt_pk_bf16_f32 v74, v74, v75
	v_exp_f32_e32 v78, v78
	v_add_f32_e32 v173, v173, v76
	v_exp_f32_e64 v79, v79
	v_mfma_f32_32x32x16_bf16 v[18:33], v[150:153], v[66:69], v[18:33]
	v_add_f32_e64 v242, v242, v77
	v_cvt_pk_bf16_f32 v75, v76, v77
	v_exp_f32_e32 v80, v80
	v_add_f32_e32 v173, v173, v78
	v_exp_f32_e64 v81, v81
	v_mfma_f32_32x32x16_bf16 v[2:17], v[146:149], v[66:69], v[2:17]
	v_add_f32_e64 v242, v242, v79
	v_cvt_pk_bf16_f32 v76, v78, v79
	v_add_f32_e32 v173, v173, v80
	v_add_f32_e32 v242, v242, v81
	v_cvt_pk_bf16_f32 v77, v80, v81
	s_waitcnt lgkmcnt(0)
	v_add_f32_e32 v173, v173, v242
	v_mfma_f32_32x32x16_bf16 v[50:65], v[238:241], v[74:77], v[50:65]
	v_mfma_f32_32x32x16_bf16 v[34:49], v[234:237], v[74:77], v[34:49]
	v_mfma_f32_32x32x16_bf16 v[18:33], v[230:233], v[74:77], v[18:33]
	v_mfma_f32_32x32x16_bf16 v[2:17], v[226:229], v[74:77], v[2:17]
	s_branch .LBB0_883
